# G1 (early LDS buffer release, 2 DMA stages in flight) + EP1 epilogue
# speedup vs baseline: 1.0324x; 1.0223x over previous
.LBB0_183:
	s_ashr_i32 s1, s0, 31
	s_lshl_b64 s[4:5], s[0:1], 18
	s_add_u32 s8, s48, s4
	s_addc_u32 s9, s49, s5
	s_ashr_i32 s45, s44, 31
	s_lshl_b64 s[6:7], s[44:45], 18
	s_waitcnt vmcnt(4)
	v_mov_b32_e32 v38, v156
	s_add_u32 s10, s22, s6
	s_addc_u32 s11, s23, s7
	v_readfirstlane_b32 s12, v38
	s_ashr_i32 s1, s12, 6
	v_bfe_u32 v0, v38, 3, 3
	v_lshl_or_b32 v2, s1, 5, v0
	v_min_i32_e32 v4, 0x7f, v2
	v_or_b32_e32 v10, 8, v2
	v_or_b32_e32 v20, 16, v2
	v_or_b32_e32 v28, 24, v2
	v_ashrrev_i32_e32 v5, 31, v4
	v_lshrrev_b32_e32 v11, 1, v10
	s_waitcnt vmcnt(1)
	v_min_i32_e32 v12, 0x7f, v10
	v_min_i32_e32 v22, 0x7f, v20
	v_min_i32_e32 v30, 0x7f, v28
	v_lshlrev_b64 v[4:5], 11, v[4:5]
	v_lshlrev_b32_e32 v0, 4, v38
	s_waitcnt vmcnt(0)
	v_and_b32_e32 v40, 48, v38
	v_ashrrev_i32_e32 v3, 31, v2
	v_xor_b32_e32 v11, v11, v38
	v_ashrrev_i32_e32 v13, 31, v12
	v_ashrrev_i32_e32 v23, 31, v22
	v_ashrrev_i32_e32 v31, 31, v30
	v_lshl_add_u64 v[4:5], s[8:9], 0, v[4:5]
	v_and_b32_e32 v41, 0x70, v0
	v_bitop3_b32 v0, v0, v40, s19 bitop3:0x6c
	v_lshlrev_b64 v[6:7], 11, v[2:3]
	v_lshlrev_b64 v[12:13], 11, v[12:13]
	v_lshlrev_b32_e32 v11, 4, v11
	v_lshlrev_b64 v[22:23], 11, v[22:23]
	v_lshrrev_b32_e32 v29, 1, v28
	v_lshlrev_b64 v[30:31], 11, v[30:31]
	s_lshl_b32 s1, s1, 12
	v_lshl_add_u64 v[4:5], v[4:5], 0, v[0:1]
	v_lshl_add_u64 v[8:9], s[10:11], 0, v[6:7]
	v_lshl_add_u64 v[12:13], s[8:9], 0, v[12:13]
	v_and_b32_e32 v14, 0x70, v11
	v_ashrrev_i32_e32 v11, 31, v10
	v_lshl_add_u64 v[22:23], s[8:9], 0, v[22:23]
	v_xor_b32_e32 v29, v29, v38
	v_lshl_add_u64 v[30:31], s[8:9], 0, v[30:31]
	s_add_i32 s8, s1, 0x4000
	s_mov_b32 m0, s1
	v_lshl_add_u64 v[8:9], v[8:9], 0, v[0:1]
	v_mov_b32_e32 v15, v1
	v_lshlrev_b64 v[16:17], 11, v[10:11]
	v_lshlrev_b32_e32 v29, 4, v29
	s_barrier
	global_load_lds_dwordx4 v[4:5], off
	s_mov_b32 m0, s8
	v_lshl_add_u64 v[12:13], v[12:13], 0, v[14:15]
	v_lshl_add_u64 v[18:19], s[10:11], 0, v[16:17]
	v_ashrrev_i32_e32 v21, 31, v20
	v_and_b32_e32 v32, 0x70, v29
	v_ashrrev_i32_e32 v29, 31, v28
	global_load_lds_dwordx4 v[8:9], off
	s_or_b32 m0, s1, 0x400
	s_add_i32 s9, s1, 0x4400
	v_lshl_add_u64 v[18:19], v[18:19], 0, v[14:15]
	v_lshlrev_b64 v[24:25], 11, v[20:21]
	v_lshlrev_b64 v[34:35], 11, v[28:29]
	global_load_lds_dwordx4 v[12:13], off
	s_mov_b32 m0, s9
	v_lshl_add_u64 v[22:23], v[22:23], 0, v[0:1]
	v_lshl_add_u64 v[26:27], s[10:11], 0, v[24:25]
	v_lshl_add_u64 v[36:37], s[10:11], 0, v[34:35]
	global_load_lds_dwordx4 v[18:19], off
	s_or_b32 m0, s1, 0x800
	s_add_i32 s10, s1, 0x4800
	v_lshl_add_u64 v[26:27], v[26:27], 0, v[0:1]
	v_mov_b32_e32 v33, v1
	global_load_lds_dwordx4 v[22:23], off
	s_mov_b32 m0, s10
	v_lshl_add_u64 v[30:31], v[30:31], 0, v[32:33]
	global_load_lds_dwordx4 v[26:27], off
	s_or_b32 m0, s1, 0xc00
	s_add_i32 s11, s1, 0x4c00
	v_lshl_add_u64 v[36:37], v[36:37], 0, v[32:33]
	global_load_lds_dwordx4 v[30:31], off
	s_mov_b32 m0, s11
	s_lshr_b32 s13, s12, 1
	global_load_lds_dwordx4 v[36:37], off
	v_and_b32_e32 v39, 31, v38
	s_and_b32 s13, s13, 0x1ffffc0
	v_or_b32_e32 v9, s13, v39
	v_cmp_gt_i64_e32 vcc, s[30:31], v[2:3]
	s_mul_i32 s13, s2, 0x7c0000
	s_add_u32 s6, s13, s6
	v_cndmask_b32_e32 v3, 0, v3, vcc
	v_cndmask_b32_e32 v2, v164, v2, vcc
	s_mul_hi_u32 s13, s2, 0x7c0000
	v_lshlrev_b64 v[2:3], 11, v[2:3]
	s_addc_u32 s7, s13, s7
	v_lshl_add_u64 v[66:67], s[4:5], 0, v[2:3]
	v_lshl_add_u64 v[2:3], s[6:7], 0, v[6:7]
	v_cmp_gt_i64_e32 vcc, s[30:31], v[10:11]
	v_lshl_add_u64 v[68:69], v[2:3], 0, v[0:1]
	v_bfe_u32 v4, v38, 5, 1
	v_cndmask_b32_e32 v3, 0, v11, vcc
	v_cndmask_b32_e32 v2, v164, v10, vcc
	v_lshlrev_b64 v[2:3], 11, v[2:3]
	v_lshrrev_b32_e32 v5, 1, v38
	v_lshl_add_u64 v[70:71], s[4:5], 0, v[2:3]
	v_lshl_add_u64 v[2:3], s[6:7], 0, v[16:17]
	v_cmp_gt_i64_e32 vcc, s[30:31], v[20:21]
	v_and_or_b32 v12, s12, 64, v39
	v_bitop3_b32 v5, v4, v5, 7 bitop3:0x78
	v_lshl_add_u64 v[72:73], v[2:3], 0, v[14:15]
	v_cndmask_b32_e32 v3, 0, v21, vcc
	v_cndmask_b32_e32 v2, v164, v20, vcc
	v_bfe_u32 v8, v38, 1, 3
	v_lshlrev_b32_e32 v9, 7, v9
	v_lshl_or_b32 v12, v12, 7, v163
	v_lshlrev_b32_e32 v5, 4, v5
	v_lshlrev_b64 v[2:3], 11, v[2:3]
	v_or_b32_e32 v98, v9, v5
	v_or_b32_e32 v99, v12, v5
	v_bitop3_b32 v5, v4, v8, 2 bitop3:0x36
	v_lshl_add_u64 v[74:75], s[4:5], 0, v[2:3]
	v_lshl_add_u64 v[2:3], s[6:7], 0, v[24:25]
	v_cmp_gt_i64_e32 vcc, s[30:31], v[28:29]
	v_lshlrev_b32_e32 v5, 4, v5
	v_lshl_add_u64 v[76:77], v[2:3], 0, v[0:1]
	v_cndmask_b32_e32 v3, 0, v29, vcc
	v_cndmask_b32_e32 v2, v164, v28, vcc
	s_waitcnt vmcnt(0)
	v_or_b32_e32 v100, v9, v5
	v_or_b32_e32 v101, v12, v5
	v_bitop3_b32 v5, v4, v8, 4 bitop3:0x36
	v_bitop3_b32 v4, v4, v8, 6 bitop3:0x36
	v_lshlrev_b64 v[2:3], 11, v[2:3]
	v_lshlrev_b32_e32 v5, 4, v5
	v_lshlrev_b32_e32 v4, 4, v4
	v_lshl_add_u64 v[78:79], s[4:5], 0, v[2:3]
	v_lshl_add_u64 v[2:3], s[6:7], 0, v[34:35]
	v_mov_b32_e32 v34, 0
	v_or_b32_e32 v102, v9, v5
	v_or_b32_e32 v103, v12, v5
	v_or_b32_e32 v104, v9, v4
	v_or_b32_e32 v105, v12, v4
	s_mov_b32 s12, 0
	v_bitop3_b32 v66, v66, v41, v40 bitop3:0xf6
	v_or_b32_e32 v70, v70, v14
	v_bitop3_b32 v74, v74, v41, v40 bitop3:0xf6
	v_or_b32_e32 v78, v78, v32
	v_lshl_add_u64 v[80:81], v[2:3], 0, v[32:33]
	s_add_i32 s6, s1, 0x8000
	s_add_i32 s7, s1, 0xc000
	s_add_i32 s13, s1, 0x8400
	s_add_i32 s14, s1, 0xc400
	s_add_i32 s15, s1, 0x8800
	s_add_i32 s16, s1, 0xc800
	s_add_i32 s17, s1, 0x8c00
	s_add_i32 s25, s1, 0xcc00
	v_mov_b32_e32 v35, v34
	v_mov_b32_e32 v36, v34
	v_mov_b32_e32 v37, v34
	v_mov_b32_e32 v38, v34
	v_mov_b32_e32 v39, v34
	v_mov_b32_e32 v40, v34
	v_mov_b32_e32 v41, v34
	v_mov_b32_e32 v42, v34
	v_mov_b32_e32 v43, v34
	v_mov_b32_e32 v44, v34
	v_mov_b32_e32 v45, v34
	v_mov_b32_e32 v46, v34
	v_mov_b32_e32 v47, v34
	v_mov_b32_e32 v48, v34
	v_mov_b32_e32 v49, v34
	v_mov_b32_e32 v2, v34
	v_mov_b32_e32 v3, v34
	v_mov_b32_e32 v4, v34
	v_mov_b32_e32 v5, v34
	v_mov_b32_e32 v6, v34
	v_mov_b32_e32 v7, v34
	v_mov_b32_e32 v8, v34
	v_mov_b32_e32 v9, v34
	v_mov_b32_e32 v10, v34
	v_mov_b32_e32 v11, v34
	v_mov_b32_e32 v12, v34
	v_mov_b32_e32 v13, v34
	v_mov_b32_e32 v14, v34
	v_mov_b32_e32 v15, v34
	v_mov_b32_e32 v16, v34
	v_mov_b32_e32 v17, v34
	v_mov_b32_e32 v50, v34
	v_mov_b32_e32 v51, v34
	v_mov_b32_e32 v52, v34
	v_mov_b32_e32 v53, v34
	v_mov_b32_e32 v54, v34
	v_mov_b32_e32 v55, v34
	v_mov_b32_e32 v56, v34
	v_mov_b32_e32 v57, v34
	v_mov_b32_e32 v58, v34
	v_mov_b32_e32 v59, v34
	v_mov_b32_e32 v60, v34
	v_mov_b32_e32 v61, v34
	v_mov_b32_e32 v62, v34
	v_mov_b32_e32 v63, v34
	v_mov_b32_e32 v64, v34
	v_mov_b32_e32 v65, v34
	v_mov_b32_e32 v18, v34
	v_mov_b32_e32 v19, v34
	v_mov_b32_e32 v20, v34
	v_mov_b32_e32 v21, v34
	v_mov_b32_e32 v22, v34
	v_mov_b32_e32 v23, v34
	v_mov_b32_e32 v24, v34
	v_mov_b32_e32 v25, v34
	v_mov_b32_e32 v26, v34
	v_mov_b32_e32 v27, v34
	v_mov_b32_e32 v28, v34
	v_mov_b32_e32 v29, v34
	v_mov_b32_e32 v30, v34
	v_mov_b32_e32 v31, v34
	v_mov_b32_e32 v32, v34
	v_mov_b32_e32 v33, v34
	s_waitcnt vmcnt(0) lgkmcnt(0)
	s_barrier
	v_lshl_add_u64 v[66:67], s[80:81], 0, v[66:67]
	v_lshl_add_u64 v[66:67], v[66:67], 0, s[64:65]
	v_lshl_add_u64 v[68:69], s[80:81], 0, v[68:69]
	v_lshl_add_u64 v[68:69], v[68:69], 0, s[66:67]
	v_lshl_add_u64 v[70:71], s[80:81], 0, v[70:71]
	v_lshl_add_u64 v[70:71], v[70:71], 0, s[64:65]
	v_lshl_add_u64 v[72:73], s[80:81], 0, v[72:73]
	v_lshl_add_u64 v[72:73], v[72:73], 0, s[66:67]
	v_lshl_add_u64 v[74:75], s[80:81], 0, v[74:75]
	v_lshl_add_u64 v[74:75], v[74:75], 0, s[64:65]
	v_lshl_add_u64 v[76:77], s[80:81], 0, v[76:77]
	v_lshl_add_u64 v[76:77], v[76:77], 0, s[66:67]
	v_lshl_add_u64 v[78:79], s[80:81], 0, v[78:79]
	v_lshl_add_u64 v[78:79], v[78:79], 0, s[64:65]
	v_lshl_add_u64 v[80:81], s[80:81], 0, v[80:81]
	v_lshl_add_u64 v[80:81], v[80:81], 0, s[66:67]
	s_mov_b32 m0, s6
	s_nop 0
	global_load_lds_dwordx4 v[66:67], off
	v_lshl_add_u64 v[66:67], v[66:67], 0, s[34:35]
	s_mov_b32 m0, s7
	s_nop 0
	global_load_lds_dwordx4 v[68:69], off
	v_lshl_add_u64 v[68:69], v[68:69], 0, s[34:35]
	s_mov_b32 m0, s13
	s_nop 0
	global_load_lds_dwordx4 v[70:71], off
	v_lshl_add_u64 v[70:71], v[70:71], 0, s[34:35]
	s_mov_b32 m0, s14
	s_nop 0
	global_load_lds_dwordx4 v[72:73], off
	v_lshl_add_u64 v[72:73], v[72:73], 0, s[34:35]
	s_mov_b32 m0, s15
	s_nop 0
	global_load_lds_dwordx4 v[74:75], off
	v_lshl_add_u64 v[74:75], v[74:75], 0, s[34:35]
	s_mov_b32 m0, s16
	s_nop 0
	global_load_lds_dwordx4 v[76:77], off
	v_lshl_add_u64 v[76:77], v[76:77], 0, s[34:35]
	s_mov_b32 m0, s17
	s_nop 0
	global_load_lds_dwordx4 v[78:79], off
	v_lshl_add_u64 v[78:79], v[78:79], 0, s[34:35]
	s_mov_b32 m0, s25
	s_nop 0
	global_load_lds_dwordx4 v[80:81], off
	v_lshl_add_u64 v[80:81], v[80:81], 0, s[34:35]
	s_mov_b32 s12, 0
.Lg1_loop:
	ds_read_b128 v[82:85], v98 offset:0
	ds_read_b128 v[90:93], v99 offset:0
	ds_read_b128 v[86:89], v98 offset:4096
	ds_read_b128 v[94:97], v99 offset:4096
	ds_read_b128 v[106:109], v100 offset:0
	ds_read_b128 v[114:117], v101 offset:0
	ds_read_b128 v[110:113], v100 offset:4096
	ds_read_b128 v[128:131], v101 offset:4096
	ds_read_b128 v[132:135], v102 offset:0
	ds_read_b128 v[140:143], v103 offset:0
	ds_read_b128 v[136:139], v102 offset:4096
	ds_read_b128 v[144:147], v103 offset:4096
	ds_read_b128 v[148:151], v104 offset:0
	ds_read_b128 v[180:183], v105 offset:0
	ds_read_b128 v[152:155], v104 offset:4096
	ds_read_b128 v[184:187], v105 offset:4096
	s_waitcnt lgkmcnt(12)
	v_mfma_f32_32x32x16_bf16 v[18:33], v[82:85], v[90:93], v[18:33]
	v_mfma_f32_32x32x16_bf16 v[50:65], v[82:85], v[94:97], v[50:65]
	v_mfma_f32_32x32x16_bf16 v[2:17], v[86:89], v[90:93], v[2:17]
	v_mfma_f32_32x32x16_bf16 v[34:49], v[86:89], v[94:97], v[34:49]
	s_waitcnt lgkmcnt(8)
	v_mfma_f32_32x32x16_bf16 v[18:33], v[106:109], v[114:117], v[18:33]
	v_mfma_f32_32x32x16_bf16 v[50:65], v[106:109], v[128:131], v[50:65]
	v_mfma_f32_32x32x16_bf16 v[2:17], v[110:113], v[114:117], v[2:17]
	v_mfma_f32_32x32x16_bf16 v[34:49], v[110:113], v[128:131], v[34:49]
	s_waitcnt lgkmcnt(0)
	s_barrier
	s_mov_b32 m0, s1
	v_mfma_f32_32x32x16_bf16 v[18:33], v[132:135], v[140:143], v[18:33]
	global_load_lds_dwordx4 v[66:67], off
	v_lshl_add_u64 v[66:67], v[66:67], 0, s[34:35]
	s_mov_b32 m0, s8
	v_mfma_f32_32x32x16_bf16 v[50:65], v[132:135], v[144:147], v[50:65]
	global_load_lds_dwordx4 v[68:69], off
	v_lshl_add_u64 v[68:69], v[68:69], 0, s[34:35]
	s_add_i32 m0, s1, 0x400
	v_mfma_f32_32x32x16_bf16 v[2:17], v[136:139], v[140:143], v[2:17]
	global_load_lds_dwordx4 v[70:71], off
	v_lshl_add_u64 v[70:71], v[70:71], 0, s[34:35]
	s_mov_b32 m0, s9
	v_mfma_f32_32x32x16_bf16 v[34:49], v[136:139], v[144:147], v[34:49]
	global_load_lds_dwordx4 v[72:73], off
	v_lshl_add_u64 v[72:73], v[72:73], 0, s[34:35]
	s_add_i32 m0, s1, 0x800
	v_mfma_f32_32x32x16_bf16 v[18:33], v[148:151], v[180:183], v[18:33]
	global_load_lds_dwordx4 v[74:75], off
	v_lshl_add_u64 v[74:75], v[74:75], 0, s[34:35]
	s_mov_b32 m0, s10
	v_mfma_f32_32x32x16_bf16 v[50:65], v[148:151], v[184:187], v[50:65]
	global_load_lds_dwordx4 v[76:77], off
	v_lshl_add_u64 v[76:77], v[76:77], 0, s[34:35]
	s_add_i32 m0, s1, 0xc00
	v_mfma_f32_32x32x16_bf16 v[2:17], v[152:155], v[180:183], v[2:17]
	global_load_lds_dwordx4 v[78:79], off
	v_lshl_add_u64 v[78:79], v[78:79], 0, s[34:35]
	s_mov_b32 m0, s11
	v_mfma_f32_32x32x16_bf16 v[34:49], v[152:155], v[184:187], v[34:49]
	global_load_lds_dwordx4 v[80:81], off
	v_lshl_add_u64 v[80:81], v[80:81], 0, s[34:35]
	s_waitcnt vmcnt(8)
	s_barrier
	ds_read_b128 v[82:85], v98 offset:32768
	ds_read_b128 v[90:93], v99 offset:32768
	ds_read_b128 v[86:89], v98 offset:36864
	ds_read_b128 v[94:97], v99 offset:36864
	ds_read_b128 v[106:109], v100 offset:32768
	ds_read_b128 v[114:117], v101 offset:32768
	ds_read_b128 v[110:113], v100 offset:36864
	ds_read_b128 v[128:131], v101 offset:36864
	ds_read_b128 v[132:135], v102 offset:32768
	ds_read_b128 v[140:143], v103 offset:32768
	ds_read_b128 v[136:139], v102 offset:36864
	ds_read_b128 v[144:147], v103 offset:36864
	ds_read_b128 v[148:151], v104 offset:32768
	ds_read_b128 v[180:183], v105 offset:32768
	ds_read_b128 v[152:155], v104 offset:36864
	ds_read_b128 v[184:187], v105 offset:36864
	s_waitcnt lgkmcnt(12)
	v_mfma_f32_32x32x16_bf16 v[18:33], v[82:85], v[90:93], v[18:33]
	v_mfma_f32_32x32x16_bf16 v[50:65], v[82:85], v[94:97], v[50:65]
	v_mfma_f32_32x32x16_bf16 v[2:17], v[86:89], v[90:93], v[2:17]
	v_mfma_f32_32x32x16_bf16 v[34:49], v[86:89], v[94:97], v[34:49]
	s_waitcnt lgkmcnt(8)
	v_mfma_f32_32x32x16_bf16 v[18:33], v[106:109], v[114:117], v[18:33]
	v_mfma_f32_32x32x16_bf16 v[50:65], v[106:109], v[128:131], v[50:65]
	v_mfma_f32_32x32x16_bf16 v[2:17], v[110:113], v[114:117], v[2:17]
	v_mfma_f32_32x32x16_bf16 v[34:49], v[110:113], v[128:131], v[34:49]
	s_waitcnt lgkmcnt(0)
	s_barrier
	s_mov_b32 m0, s6
	v_mfma_f32_32x32x16_bf16 v[18:33], v[132:135], v[140:143], v[18:33]
	global_load_lds_dwordx4 v[66:67], off
	v_lshl_add_u64 v[66:67], v[66:67], 0, s[34:35]
	s_mov_b32 m0, s7
	v_mfma_f32_32x32x16_bf16 v[50:65], v[132:135], v[144:147], v[50:65]
	global_load_lds_dwordx4 v[68:69], off
	v_lshl_add_u64 v[68:69], v[68:69], 0, s[34:35]
	s_mov_b32 m0, s13
	v_mfma_f32_32x32x16_bf16 v[2:17], v[136:139], v[140:143], v[2:17]
	global_load_lds_dwordx4 v[70:71], off
	v_lshl_add_u64 v[70:71], v[70:71], 0, s[34:35]
	s_mov_b32 m0, s14
	v_mfma_f32_32x32x16_bf16 v[34:49], v[136:139], v[144:147], v[34:49]
	global_load_lds_dwordx4 v[72:73], off
	v_lshl_add_u64 v[72:73], v[72:73], 0, s[34:35]
	s_mov_b32 m0, s15
	v_mfma_f32_32x32x16_bf16 v[18:33], v[148:151], v[180:183], v[18:33]
	global_load_lds_dwordx4 v[74:75], off
	v_lshl_add_u64 v[74:75], v[74:75], 0, s[34:35]
	s_mov_b32 m0, s16
	v_mfma_f32_32x32x16_bf16 v[50:65], v[148:151], v[184:187], v[50:65]
	global_load_lds_dwordx4 v[76:77], off
	v_lshl_add_u64 v[76:77], v[76:77], 0, s[34:35]
	s_mov_b32 m0, s17
	v_mfma_f32_32x32x16_bf16 v[2:17], v[152:155], v[180:183], v[2:17]
	global_load_lds_dwordx4 v[78:79], off
	v_lshl_add_u64 v[78:79], v[78:79], 0, s[34:35]
	s_mov_b32 m0, s25
	v_mfma_f32_32x32x16_bf16 v[34:49], v[152:155], v[184:187], v[34:49]
	global_load_lds_dwordx4 v[80:81], off
	v_lshl_add_u64 v[80:81], v[80:81], 0, s[34:35]
	s_waitcnt vmcnt(8)
	s_barrier
	s_add_i32 s12, s12, 2
	s_cmp_lt_u32 s12, 14
	s_cbranch_scc1 .Lg1_loop
	ds_read_b128 v[82:85], v98 offset:0
	ds_read_b128 v[90:93], v99 offset:0
	ds_read_b128 v[86:89], v98 offset:4096
	ds_read_b128 v[94:97], v99 offset:4096
	ds_read_b128 v[106:109], v100 offset:0
	ds_read_b128 v[114:117], v101 offset:0
	ds_read_b128 v[110:113], v100 offset:4096
	ds_read_b128 v[128:131], v101 offset:4096
	ds_read_b128 v[132:135], v102 offset:0
	ds_read_b128 v[140:143], v103 offset:0
	ds_read_b128 v[136:139], v102 offset:4096
	ds_read_b128 v[144:147], v103 offset:4096
	ds_read_b128 v[148:151], v104 offset:0
	ds_read_b128 v[180:183], v105 offset:0
	ds_read_b128 v[152:155], v104 offset:4096
	ds_read_b128 v[184:187], v105 offset:4096
	s_waitcnt lgkmcnt(12)
	v_mfma_f32_32x32x16_bf16 v[18:33], v[82:85], v[90:93], v[18:33]
	v_mfma_f32_32x32x16_bf16 v[50:65], v[82:85], v[94:97], v[50:65]
	v_mfma_f32_32x32x16_bf16 v[2:17], v[86:89], v[90:93], v[2:17]
	v_mfma_f32_32x32x16_bf16 v[34:49], v[86:89], v[94:97], v[34:49]
	s_waitcnt lgkmcnt(8)
	v_mfma_f32_32x32x16_bf16 v[18:33], v[106:109], v[114:117], v[18:33]
	v_mfma_f32_32x32x16_bf16 v[50:65], v[106:109], v[128:131], v[50:65]
	v_mfma_f32_32x32x16_bf16 v[2:17], v[110:113], v[114:117], v[2:17]
	v_mfma_f32_32x32x16_bf16 v[34:49], v[110:113], v[128:131], v[34:49]
	s_waitcnt lgkmcnt(0)
	s_barrier
	v_mfma_f32_32x32x16_bf16 v[18:33], v[132:135], v[140:143], v[18:33]
	v_mfma_f32_32x32x16_bf16 v[50:65], v[132:135], v[144:147], v[50:65]
	v_mfma_f32_32x32x16_bf16 v[2:17], v[136:139], v[140:143], v[2:17]
	v_mfma_f32_32x32x16_bf16 v[34:49], v[136:139], v[144:147], v[34:49]
	v_mfma_f32_32x32x16_bf16 v[18:33], v[148:151], v[180:183], v[18:33]
	v_mfma_f32_32x32x16_bf16 v[50:65], v[148:151], v[184:187], v[50:65]
	v_mfma_f32_32x32x16_bf16 v[2:17], v[152:155], v[180:183], v[2:17]
	v_mfma_f32_32x32x16_bf16 v[34:49], v[152:155], v[184:187], v[34:49]
	s_waitcnt vmcnt(0)
	s_barrier
	ds_read_b128 v[82:85], v98 offset:32768
	ds_read_b128 v[90:93], v99 offset:32768
	ds_read_b128 v[86:89], v98 offset:36864
	ds_read_b128 v[94:97], v99 offset:36864
	ds_read_b128 v[106:109], v100 offset:32768
	ds_read_b128 v[114:117], v101 offset:32768
	ds_read_b128 v[110:113], v100 offset:36864
	ds_read_b128 v[128:131], v101 offset:36864
	ds_read_b128 v[132:135], v102 offset:32768
	ds_read_b128 v[140:143], v103 offset:32768
	ds_read_b128 v[136:139], v102 offset:36864
	ds_read_b128 v[144:147], v103 offset:36864
	ds_read_b128 v[148:151], v104 offset:32768
	ds_read_b128 v[180:183], v105 offset:32768
	ds_read_b128 v[152:155], v104 offset:36864
	ds_read_b128 v[184:187], v105 offset:36864
	s_waitcnt lgkmcnt(12)
	v_mfma_f32_32x32x16_bf16 v[18:33], v[82:85], v[90:93], v[18:33]
	v_mfma_f32_32x32x16_bf16 v[50:65], v[82:85], v[94:97], v[50:65]
	v_mfma_f32_32x32x16_bf16 v[2:17], v[86:89], v[90:93], v[2:17]
	v_mfma_f32_32x32x16_bf16 v[34:49], v[86:89], v[94:97], v[34:49]
	s_waitcnt lgkmcnt(8)
	v_mfma_f32_32x32x16_bf16 v[18:33], v[106:109], v[114:117], v[18:33]
	v_mfma_f32_32x32x16_bf16 v[50:65], v[106:109], v[128:131], v[50:65]
	v_mfma_f32_32x32x16_bf16 v[2:17], v[110:113], v[114:117], v[2:17]
	v_mfma_f32_32x32x16_bf16 v[34:49], v[110:113], v[128:131], v[34:49]
	s_waitcnt lgkmcnt(0)
	s_barrier
	v_mfma_f32_32x32x16_bf16 v[18:33], v[132:135], v[140:143], v[18:33]
	v_mfma_f32_32x32x16_bf16 v[50:65], v[132:135], v[144:147], v[50:65]
	v_mfma_f32_32x32x16_bf16 v[2:17], v[136:139], v[140:143], v[2:17]
	v_mfma_f32_32x32x16_bf16 v[34:49], v[136:139], v[144:147], v[34:49]
	v_mfma_f32_32x32x16_bf16 v[18:33], v[148:151], v[180:183], v[18:33]
	v_mfma_f32_32x32x16_bf16 v[50:65], v[148:151], v[184:187], v[50:65]
	v_mfma_f32_32x32x16_bf16 v[2:17], v[152:155], v[180:183], v[2:17]
	v_mfma_f32_32x32x16_bf16 v[34:49], v[152:155], v[184:187], v[34:49]
	s_waitcnt vmcnt(0) lgkmcnt(0)
	s_barrier
